# snake order in all GEMM loops plus P1 loop fragment registers renamed for operand alignment
# speedup vs baseline: 1.0230x; 1.0034x over previous
.LBB0_211:
	ds_read_b128 v[228:231], v153
	ds_read_b128 v[162:165], v153 offset:1024
	ds_read_b128 v[224:227], v153 offset:2048
	ds_read_b128 v[166:169], v153 offset:3072
	ds_read_b128 v[220:223], v157
	ds_read_b128 v[174:177], v157 offset:1024
	ds_read_b128 v[216:219], v157 offset:2048
	ds_read_b128 v[178:181], v157 offset:3072
	s_add_u32 s20, s52, 0xfff00080
	s_addc_u32 s21, s53, -1
	s_cmp_eq_u32 s77, 60
	s_cselect_b32 s57, s17, s21
	s_cselect_b32 s56, s41, s20
	s_cselect_b32 s55, s15, s76
	s_cselect_b32 s54, s74, s75
	v_lshl_add_u64 v[144:145], s[52:53], 0, v[140:141]
	s_add_i32 m0, s62, 0xc000
	ds_read_b128 v[182:185], v158
	ds_read_b128 v[186:189], v158 offset:1024
	ds_read_b128 v[190:193], v158 offset:2048
	ds_read_b128 v[194:197], v158 offset:3072
	ds_read_b128 v[198:201], v158 offset:4096
	ds_read_b128 v[202:205], v158 offset:5120
	ds_read_b128 v[206:209], v158 offset:6144
	ds_read_b128 v[210:213], v158 offset:7168
	global_load_lds_dwordx4 v[144:145], off
	v_lshl_add_u64 v[144:145], s[52:53], 0, v[142:143]
	s_add_i32 m0, s62, 0xe000
	s_nop 0
	global_load_lds_dwordx4 v[144:145], off
	s_waitcnt vmcnt(8)
	s_waitcnt lgkmcnt(0)
	s_barrier
	s_setprio 1
	s_waitcnt lgkmcnt(0)
	v_mfma_f32_16x16x32_bf16 v[126:129], v[228:231], v[182:185], v[126:129]
	v_mfma_f32_16x16x32_bf16 v[126:129], v[162:165], v[186:189], v[126:129]
	v_mfma_f32_16x16x32_bf16 v[118:121], v[224:227], v[182:185], v[118:121]
	v_mfma_f32_16x16x32_bf16 v[118:121], v[166:169], v[186:189], v[118:121]
	v_mfma_f32_16x16x32_bf16 v[106:109], v[224:227], v[190:193], v[106:109]
	v_mfma_f32_16x16x32_bf16 v[106:109], v[166:169], v[194:197], v[106:109]
	v_mfma_f32_16x16x32_bf16 v[110:113], v[228:231], v[190:193], v[110:113]
	v_mfma_f32_16x16x32_bf16 v[110:113], v[162:165], v[194:197], v[110:113]
	v_mfma_f32_16x16x32_bf16 v[94:97], v[228:231], v[198:201], v[94:97]
	v_mfma_f32_16x16x32_bf16 v[94:97], v[162:165], v[202:205], v[94:97]
	v_mfma_f32_16x16x32_bf16 v[90:93], v[224:227], v[198:201], v[90:93]
	v_mfma_f32_16x16x32_bf16 v[90:93], v[166:169], v[202:205], v[90:93]
	v_mfma_f32_16x16x32_bf16 v[74:77], v[224:227], v[206:209], v[74:77]
	v_mfma_f32_16x16x32_bf16 v[74:77], v[166:169], v[210:213], v[74:77]
	v_mfma_f32_16x16x32_bf16 v[78:81], v[228:231], v[206:209], v[78:81]
	v_mfma_f32_16x16x32_bf16 v[78:81], v[162:165], v[210:213], v[78:81]
	s_setprio 0
	s_setprio 1
	v_mfma_f32_16x16x32_bf16 v[122:125], v[220:223], v[182:185], v[122:125]
	v_mfma_f32_16x16x32_bf16 v[122:125], v[174:177], v[186:189], v[122:125]
	v_mfma_f32_16x16x32_bf16 v[114:117], v[216:219], v[182:185], v[114:117]
	v_mfma_f32_16x16x32_bf16 v[114:117], v[178:181], v[186:189], v[114:117]
	v_mfma_f32_16x16x32_bf16 v[98:101], v[216:219], v[190:193], v[98:101]
	v_mfma_f32_16x16x32_bf16 v[98:101], v[178:181], v[194:197], v[98:101]
	v_mfma_f32_16x16x32_bf16 v[102:105], v[220:223], v[190:193], v[102:105]
	v_mfma_f32_16x16x32_bf16 v[102:105], v[174:177], v[194:197], v[102:105]
	v_mfma_f32_16x16x32_bf16 v[86:89], v[220:223], v[198:201], v[86:89]
	v_mfma_f32_16x16x32_bf16 v[86:89], v[174:177], v[202:205], v[86:89]
	v_mfma_f32_16x16x32_bf16 v[82:85], v[216:219], v[198:201], v[82:85]
	v_mfma_f32_16x16x32_bf16 v[82:85], v[178:181], v[202:205], v[82:85]
	v_mfma_f32_16x16x32_bf16 v[66:69], v[216:219], v[206:209], v[66:69]
	v_mfma_f32_16x16x32_bf16 v[66:69], v[178:181], v[210:213], v[66:69]
	v_mfma_f32_16x16x32_bf16 v[70:73], v[220:223], v[206:209], v[70:73]
	v_mfma_f32_16x16x32_bf16 v[70:73], v[174:177], v[210:213], v[70:73]
	s_setprio 0
	s_barrier
	s_add_i32 s20, s72, s33
	v_lshl_add_u64 v[144:145], s[54:55], 0, v[132:133]
	s_mov_b32 m0, s20
	ds_read_b128 v[182:185], v158 offset:16384
	ds_read_b128 v[186:189], v158 offset:17408
	ds_read_b128 v[190:193], v158 offset:18432
	ds_read_b128 v[194:197], v158 offset:19456
	ds_read_b128 v[198:201], v158 offset:20480
	ds_read_b128 v[202:205], v158 offset:21504
	ds_read_b128 v[206:209], v158 offset:22528
	ds_read_b128 v[210:213], v158 offset:23552
	global_load_lds_dwordx4 v[144:145], off
	s_add_i32 m0, s20, 0x2000
	s_add_u32 s20, s54, 0x100000
	v_lshl_add_u64 v[160:161], s[54:55], 0, v[136:137]
	s_addc_u32 s21, s55, 0
	s_add_i32 s22, s73, s33
	global_load_lds_dwordx4 v[160:161], off
	v_lshl_add_u64 v[172:173], s[20:21], 0, v[132:133]
	s_mov_b32 m0, s22
	v_lshl_add_u64 v[214:215], s[56:57], 0, v[134:135]
	global_load_lds_dwordx4 v[172:173], off
	v_lshl_add_u64 v[172:173], s[20:21], 0, v[136:137]
	s_add_i32 m0, s22, 0x2000
	s_nop 0
	global_load_lds_dwordx4 v[172:173], off
	v_lshl_add_u64 v[172:173], s[56:57], 0, v[130:131]
	s_mov_b32 m0, s62
	s_nop 0
	global_load_lds_dwordx4 v[172:173], off
	s_mov_b32 m0, s63
	s_nop 0
	global_load_lds_dwordx4 v[214:215], off
	s_waitcnt vmcnt(8)
	s_waitcnt lgkmcnt(0)
	s_barrier
	s_setprio 1
	s_waitcnt lgkmcnt(0)
	v_mfma_f32_16x16x32_bf16 v[62:65], v[228:231], v[182:185], v[62:65]
	v_mfma_f32_16x16x32_bf16 v[62:65], v[162:165], v[186:189], v[62:65]
	v_mfma_f32_16x16x32_bf16 v[58:61], v[224:227], v[182:185], v[58:61]
	v_mfma_f32_16x16x32_bf16 v[58:61], v[166:169], v[186:189], v[58:61]
	v_mfma_f32_16x16x32_bf16 v[42:45], v[224:227], v[190:193], v[42:45]
	v_mfma_f32_16x16x32_bf16 v[42:45], v[166:169], v[194:197], v[42:45]
	v_mfma_f32_16x16x32_bf16 v[50:53], v[228:231], v[190:193], v[50:53]
	v_mfma_f32_16x16x32_bf16 v[50:53], v[162:165], v[194:197], v[50:53]
	v_mfma_f32_16x16x32_bf16 v[34:37], v[228:231], v[198:201], v[34:37]
	v_mfma_f32_16x16x32_bf16 v[34:37], v[162:165], v[202:205], v[34:37]
	v_mfma_f32_16x16x32_bf16 v[26:29], v[224:227], v[198:201], v[26:29]
	v_mfma_f32_16x16x32_bf16 v[26:29], v[166:169], v[202:205], v[26:29]
	v_mfma_f32_16x16x32_bf16 v[6:9], v[224:227], v[206:209], v[6:9]
	v_mfma_f32_16x16x32_bf16 v[6:9], v[166:169], v[210:213], v[6:9]
	v_mfma_f32_16x16x32_bf16 v[14:17], v[228:231], v[206:209], v[14:17]
	v_mfma_f32_16x16x32_bf16 v[14:17], v[162:165], v[210:213], v[14:17]
	s_setprio 0
	s_setprio 1
	v_mfma_f32_16x16x32_bf16 v[54:57], v[220:223], v[182:185], v[54:57]
	v_mfma_f32_16x16x32_bf16 v[54:57], v[174:177], v[186:189], v[54:57]
	v_mfma_f32_16x16x32_bf16 v[46:49], v[216:219], v[182:185], v[46:49]
	v_mfma_f32_16x16x32_bf16 v[46:49], v[178:181], v[186:189], v[46:49]
	v_mfma_f32_16x16x32_bf16 v[30:33], v[216:219], v[190:193], v[30:33]
	v_mfma_f32_16x16x32_bf16 v[30:33], v[178:181], v[194:197], v[30:33]
	v_mfma_f32_16x16x32_bf16 v[38:41], v[220:223], v[190:193], v[38:41]
	v_mfma_f32_16x16x32_bf16 v[38:41], v[174:177], v[194:197], v[38:41]
	v_mfma_f32_16x16x32_bf16 v[22:25], v[220:223], v[198:201], v[22:25]
	v_mfma_f32_16x16x32_bf16 v[22:25], v[174:177], v[202:205], v[22:25]
	v_mfma_f32_16x16x32_bf16 v[18:21], v[216:219], v[198:201], v[18:21]
	v_mfma_f32_16x16x32_bf16 v[18:21], v[178:181], v[202:205], v[18:21]
	v_mfma_f32_16x16x32_bf16 v[2:5], v[216:219], v[206:209], v[2:5]
	v_mfma_f32_16x16x32_bf16 v[2:5], v[178:181], v[210:213], v[2:5]
	v_mfma_f32_16x16x32_bf16 v[10:13], v[220:223], v[206:209], v[10:13]
	v_mfma_f32_16x16x32_bf16 v[10:13], v[174:177], v[210:213], v[10:13]
	s_setprio 0
	s_barrier
	s_add_i32 s22, 0, 0x18000
	v_add_u32_e32 v159, s22, v150
	s_add_i32 s23, 0, 0x1c000
	ds_read_b128 v[228:231], v159
	ds_read_b128 v[162:165], v159 offset:1024
	ds_read_b128 v[224:227], v159 offset:2048
	ds_read_b128 v[166:169], v159 offset:3072
	v_add_u32_e32 v159, s23, v150
	ds_read_b128 v[220:223], v159
	ds_read_b128 v[174:177], v159 offset:1024
	ds_read_b128 v[216:219], v159 offset:2048
	ds_read_b128 v[178:181], v159 offset:3072
	s_add_u32 s20, s56, 0x100000
	s_addc_u32 s21, s57, 0
	s_mov_b32 m0, s64
	v_lshl_add_u64 v[232:233], s[20:21], 0, v[130:131]
	ds_read_b128 v[182:185], v158 offset:32768
	ds_read_b128 v[186:189], v158 offset:33792
	ds_read_b128 v[190:193], v158 offset:34816
	ds_read_b128 v[194:197], v158 offset:35840
	ds_read_b128 v[198:201], v158 offset:36864
	ds_read_b128 v[202:205], v158 offset:37888
	ds_read_b128 v[206:209], v158 offset:38912
	ds_read_b128 v[210:213], v158 offset:39936
	global_load_lds_dwordx4 v[232:233], off
	v_lshl_add_u64 v[232:233], s[20:21], 0, v[134:135]
	s_mov_b32 m0, s65
	s_nop 0
	global_load_lds_dwordx4 v[232:233], off
	s_waitcnt vmcnt(8)
	s_waitcnt lgkmcnt(0)
	s_barrier
	s_setprio 1
	s_waitcnt lgkmcnt(0)
	v_mfma_f32_16x16x32_bf16 v[126:129], v[228:231], v[182:185], v[126:129]
	v_mfma_f32_16x16x32_bf16 v[126:129], v[162:165], v[186:189], v[126:129]
	v_mfma_f32_16x16x32_bf16 v[118:121], v[224:227], v[182:185], v[118:121]
	v_mfma_f32_16x16x32_bf16 v[118:121], v[166:169], v[186:189], v[118:121]
	v_mfma_f32_16x16x32_bf16 v[106:109], v[224:227], v[190:193], v[106:109]
	v_mfma_f32_16x16x32_bf16 v[106:109], v[166:169], v[194:197], v[106:109]
	v_mfma_f32_16x16x32_bf16 v[110:113], v[228:231], v[190:193], v[110:113]
	v_mfma_f32_16x16x32_bf16 v[110:113], v[162:165], v[194:197], v[110:113]
	v_mfma_f32_16x16x32_bf16 v[94:97], v[228:231], v[198:201], v[94:97]
	v_mfma_f32_16x16x32_bf16 v[94:97], v[162:165], v[202:205], v[94:97]
	v_mfma_f32_16x16x32_bf16 v[90:93], v[224:227], v[198:201], v[90:93]
	v_mfma_f32_16x16x32_bf16 v[90:93], v[166:169], v[202:205], v[90:93]
	v_mfma_f32_16x16x32_bf16 v[74:77], v[224:227], v[206:209], v[74:77]
	v_mfma_f32_16x16x32_bf16 v[74:77], v[166:169], v[210:213], v[74:77]
	v_mfma_f32_16x16x32_bf16 v[78:81], v[228:231], v[206:209], v[78:81]
	v_mfma_f32_16x16x32_bf16 v[78:81], v[162:165], v[210:213], v[78:81]
	s_setprio 0
	s_setprio 1
	v_mfma_f32_16x16x32_bf16 v[122:125], v[220:223], v[182:185], v[122:125]
	v_mfma_f32_16x16x32_bf16 v[122:125], v[174:177], v[186:189], v[122:125]
	v_mfma_f32_16x16x32_bf16 v[114:117], v[216:219], v[182:185], v[114:117]
	v_mfma_f32_16x16x32_bf16 v[114:117], v[178:181], v[186:189], v[114:117]
	v_mfma_f32_16x16x32_bf16 v[98:101], v[216:219], v[190:193], v[98:101]
	v_mfma_f32_16x16x32_bf16 v[98:101], v[178:181], v[194:197], v[98:101]
	v_mfma_f32_16x16x32_bf16 v[102:105], v[220:223], v[190:193], v[102:105]
	v_mfma_f32_16x16x32_bf16 v[102:105], v[174:177], v[194:197], v[102:105]
	v_mfma_f32_16x16x32_bf16 v[86:89], v[220:223], v[198:201], v[86:89]
	v_mfma_f32_16x16x32_bf16 v[86:89], v[174:177], v[202:205], v[86:89]
	v_mfma_f32_16x16x32_bf16 v[82:85], v[216:219], v[198:201], v[82:85]
	v_mfma_f32_16x16x32_bf16 v[82:85], v[178:181], v[202:205], v[82:85]
	v_mfma_f32_16x16x32_bf16 v[66:69], v[216:219], v[206:209], v[66:69]
	v_mfma_f32_16x16x32_bf16 v[66:69], v[178:181], v[210:213], v[66:69]
	v_mfma_f32_16x16x32_bf16 v[70:73], v[220:223], v[206:209], v[70:73]
	v_mfma_f32_16x16x32_bf16 v[70:73], v[174:177], v[210:213], v[70:73]
	s_setprio 0
	s_barrier
	s_add_i32 s20, s22, s33
	v_lshl_add_u64 v[144:145], v[144:145], 0, s[8:9]
	s_mov_b32 m0, s20
	ds_read_b128 v[182:185], v158 offset:49152
	ds_read_b128 v[186:189], v158 offset:50176
	ds_read_b128 v[190:193], v158 offset:51200
	ds_read_b128 v[194:197], v158 offset:52224
	ds_read_b128 v[198:201], v158 offset:53248
	ds_read_b128 v[202:205], v158 offset:54272
	ds_read_b128 v[206:209], v158 offset:55296
	ds_read_b128 v[210:213], v158 offset:56320
	global_load_lds_dwordx4 v[144:145], off
	s_add_i32 m0, s20, 0x2000
	s_add_u32 s20, s54, 0x100080
	v_lshl_add_u64 v[144:145], v[160:161], 0, s[8:9]
	s_addc_u32 s21, s55, 0
	s_add_i32 s22, s23, s33
	global_load_lds_dwordx4 v[144:145], off
	v_lshl_add_u64 v[144:145], s[20:21], 0, v[132:133]
	s_mov_b32 m0, s22
	s_nop 0
	global_load_lds_dwordx4 v[144:145], off
	v_lshl_add_u64 v[144:145], s[20:21], 0, v[136:137]
	s_add_i32 m0, s22, 0x2000
	s_nop 0
	global_load_lds_dwordx4 v[144:145], off
	v_lshl_add_u64 v[144:145], v[172:173], 0, s[8:9]
	s_mov_b32 m0, s66
	s_nop 0
	global_load_lds_dwordx4 v[144:145], off
	v_lshl_add_u64 v[144:145], v[214:215], 0, s[8:9]
	s_mov_b32 m0, s67
	s_nop 0
	global_load_lds_dwordx4 v[144:145], off
	s_waitcnt vmcnt(8)
	s_waitcnt lgkmcnt(0)
	s_barrier
	s_setprio 1
	s_waitcnt lgkmcnt(0)
	v_mfma_f32_16x16x32_bf16 v[62:65], v[228:231], v[182:185], v[62:65]
	v_mfma_f32_16x16x32_bf16 v[62:65], v[162:165], v[186:189], v[62:65]
	v_mfma_f32_16x16x32_bf16 v[58:61], v[224:227], v[182:185], v[58:61]
	v_mfma_f32_16x16x32_bf16 v[58:61], v[166:169], v[186:189], v[58:61]
	v_mfma_f32_16x16x32_bf16 v[42:45], v[224:227], v[190:193], v[42:45]
	v_mfma_f32_16x16x32_bf16 v[42:45], v[166:169], v[194:197], v[42:45]
	v_mfma_f32_16x16x32_bf16 v[50:53], v[228:231], v[190:193], v[50:53]
	v_mfma_f32_16x16x32_bf16 v[50:53], v[162:165], v[194:197], v[50:53]
	v_mfma_f32_16x16x32_bf16 v[34:37], v[228:231], v[198:201], v[34:37]
	v_mfma_f32_16x16x32_bf16 v[34:37], v[162:165], v[202:205], v[34:37]
	v_mfma_f32_16x16x32_bf16 v[26:29], v[224:227], v[198:201], v[26:29]
	v_mfma_f32_16x16x32_bf16 v[26:29], v[166:169], v[202:205], v[26:29]
	v_mfma_f32_16x16x32_bf16 v[6:9], v[224:227], v[206:209], v[6:9]
	v_mfma_f32_16x16x32_bf16 v[6:9], v[166:169], v[210:213], v[6:9]
	v_mfma_f32_16x16x32_bf16 v[14:17], v[228:231], v[206:209], v[14:17]
	v_mfma_f32_16x16x32_bf16 v[14:17], v[162:165], v[210:213], v[14:17]
	s_setprio 0
	s_setprio 1
	v_mfma_f32_16x16x32_bf16 v[54:57], v[220:223], v[182:185], v[54:57]
	v_mfma_f32_16x16x32_bf16 v[54:57], v[174:177], v[186:189], v[54:57]
	v_mfma_f32_16x16x32_bf16 v[46:49], v[216:219], v[182:185], v[46:49]
	v_mfma_f32_16x16x32_bf16 v[46:49], v[178:181], v[186:189], v[46:49]
	v_mfma_f32_16x16x32_bf16 v[30:33], v[216:219], v[190:193], v[30:33]
	v_mfma_f32_16x16x32_bf16 v[30:33], v[178:181], v[194:197], v[30:33]
	v_mfma_f32_16x16x32_bf16 v[38:41], v[220:223], v[190:193], v[38:41]
	v_mfma_f32_16x16x32_bf16 v[38:41], v[174:177], v[194:197], v[38:41]
	v_mfma_f32_16x16x32_bf16 v[22:25], v[220:223], v[198:201], v[22:25]
	v_mfma_f32_16x16x32_bf16 v[22:25], v[174:177], v[202:205], v[22:25]
	v_mfma_f32_16x16x32_bf16 v[18:21], v[216:219], v[198:201], v[18:21]
	v_mfma_f32_16x16x32_bf16 v[18:21], v[178:181], v[202:205], v[18:21]
	v_mfma_f32_16x16x32_bf16 v[2:5], v[216:219], v[206:209], v[2:5]
	v_mfma_f32_16x16x32_bf16 v[2:5], v[178:181], v[210:213], v[2:5]
	v_mfma_f32_16x16x32_bf16 v[10:13], v[220:223], v[206:209], v[10:13]
	v_mfma_f32_16x16x32_bf16 v[10:13], v[174:177], v[210:213], v[10:13]
	s_setprio 0
	s_barrier
	s_add_i32 s77, s77, 2
	s_add_u32 s52, s52, 0x100
	s_addc_u32 s53, s53, 0
	s_add_u32 s75, s75, 0x100
	s_addc_u32 s76, s76, 0
	s_cmp_gt_u32 s77, 61
	s_cbranch_scc0 .LBB0_211
	s_and_b64 vcc, exec, s[10:11]
	s_cbranch_vccz .LBB0_214
	s_barrier
